# S10 RMSNorm (bf16 output) row loop software-pipelined over two rows as S7
# speedup vs baseline: 1.0022x; 1.0022x over previous
.LBB0_1448:
	v_readfirstlane_b32 s17, v18
	s_lshl_b32 s32, s8, 1
	s_lshl_b64 s[80:81], s[46:47], 1
	global_load_dwordx4 v[22:25], v[20:21], off
	global_load_dwordx4 v[28:31], v[20:21], off offset:1024
	s_add_i32 s23, s17, s8
	s_cmp_lt_i32 s23, 0x8000
	s_cselect_b32 s18, s46, 0
	s_cselect_b32 s19, s47, 0
	v_lshl_add_u64 v[204:205], v[20:21], 0, s[18:19]
	global_load_dwordx4 v[222:225], v[204:205], off
	global_load_dwordx4 v[228:231], v[204:205], off offset:1024
	s_waitcnt vmcnt(2)
	s_branch .Lnorm_s10_a

.Lnorm_s10_a:
	v_and_b32_e32 v41, 0xffff0000, v22
	v_lshlrev_b32_e32 v40, 16, v22
	v_mul_f32_e32 v0, v41, v41
	v_lshlrev_b32_e32 v42, 16, v23
	v_fmac_f32_e32 v0, v40, v40
	v_and_b32_e32 v43, 0xffff0000, v23
	v_fmac_f32_e32 v0, v42, v42
	v_lshlrev_b32_e32 v44, 16, v24
	v_fmac_f32_e32 v0, v43, v43
	v_and_b32_e32 v45, 0xffff0000, v24
	v_fmac_f32_e32 v0, v44, v44
	v_lshlrev_b32_e32 v46, 16, v25
	v_fmac_f32_e32 v0, v45, v45
	v_and_b32_e32 v47, 0xffff0000, v25
	v_fmac_f32_e32 v0, v46, v46
	v_fmac_f32_e32 v0, v47, v47
	v_lshlrev_b32_e32 v22, 16, v28
	v_and_b32_e32 v23, 0xffff0000, v28
	v_fmac_f32_e32 v0, v22, v22
	v_lshlrev_b32_e32 v24, 16, v29
	v_fmac_f32_e32 v0, v23, v23
	v_and_b32_e32 v26, 0xffff0000, v30
	v_and_b32_e32 v25, 0xffff0000, v29
	v_fmac_f32_e32 v0, v24, v24
	v_lshlrev_b32_e32 v29, 16, v30
	v_mov_b32_e32 v28, v26
	v_fmac_f32_e32 v0, v25, v25
	v_pk_mul_f32 v[48:49], v[28:29], v[28:29]
	v_and_b32_e32 v27, s0, v31
	v_add_f32_e32 v0, v49, v0
	v_add_f32_e32 v19, v48, v0
	v_and_b32_e32 v0, 0xffff0000, v31
	v_lshlrev_b32_e32 v31, 16, v31
	v_mov_b32_e32 v30, v0
	v_pk_mul_f32 v[48:49], v[30:31], v[30:31]
	v_pk_mov_b32 v[26:27], v[28:29], v[26:27] op_sel:[1,0]
	v_add_f32_e32 v19, v49, v19
	v_add_f32_e32 v19, v48, v19
	ds_bpermute_b32 v32, v33, v19
	v_pk_mov_b32 v[28:29], v[30:31], v[0:1] op_sel:[1,0]
	s_waitcnt lgkmcnt(0)
	v_add_f32_e32 v19, v19, v32
	ds_bpermute_b32 v32, v34, v19
	s_waitcnt lgkmcnt(0)
	v_add_f32_e32 v19, v19, v32
	ds_bpermute_b32 v32, v35, v19
	s_waitcnt lgkmcnt(0)
	v_add_f32_e32 v19, v19, v32
	ds_bpermute_b32 v32, v36, v19
	s_waitcnt lgkmcnt(0)
	v_add_f32_e32 v19, v19, v32
	ds_bpermute_b32 v32, v37, v19
	s_waitcnt lgkmcnt(0)
	v_add_f32_e32 v19, v19, v32
	ds_bpermute_b32 v32, v38, v19
	s_waitcnt lgkmcnt(0)
	v_add_f32_e32 v19, v19, v32
	v_fmamk_f32 v19, v19, 0x3a800000, v194
	v_cmp_gt_f32_e32 vcc, s76, v19
	v_mul_f32_e32 v32, 0x4b800000, v19
	s_nop 0
	v_cndmask_b32_e32 v19, v19, v32, vcc
	v_rsq_f32_e32 v19, v19
	s_nop 0
	v_mul_f32_e32 v32, 0x45800000, v19
	v_cndmask_b32_e32 v32, v19, v32, vcc
	v_pk_mul_f32 v[40:41], v[40:41], v[32:33] op_sel_hi:[1,0]
	v_pk_mul_f32 v[42:43], v[42:43], v[32:33] op_sel_hi:[1,0]
	v_pk_mul_f32 v[44:45], v[44:45], v[32:33] op_sel_hi:[1,0]
	v_pk_mul_f32 v[42:43], v[8:9], v[42:43]
	v_pk_mul_f32 v[40:41], v[6:7], v[40:41]
	v_pk_mul_f32 v[44:45], v[2:3], v[44:45]
	v_cvt_pk_bf16_f32 v40, v40, v41
	v_cvt_pk_bf16_f32 v41, v42, v43
	v_cvt_pk_bf16_f32 v42, v44, v45
	v_add_co_u32_e32 v44, vcc, s2, v20
	v_pk_mul_f32 v[22:23], v[22:23], v[32:33] op_sel_hi:[1,0]
	v_pk_mul_f32 v[24:25], v[24:25], v[32:33] op_sel_hi:[1,0]
	v_pk_mul_f32 v[26:27], v[32:33], v[26:27] op_sel_hi:[0,1]
	v_addc_co_u32_e32 v45, vcc, -1, v21, vcc
	v_pk_mul_f32 v[24:25], v[16:17], v[24:25]
	v_pk_mul_f32 v[22:23], v[14:15], v[22:23]
	v_pk_mul_f32 v[26:27], v[10:11], v[26:27]
	v_cvt_pk_bf16_f32 v22, v22, v23
	v_cvt_pk_bf16_f32 v23, v24, v25
	v_cvt_pk_bf16_f32 v24, v26, v27
	v_add_co_u32_e32 v26, vcc, 0xea67e000, v20
	v_pk_mul_f32 v[46:47], v[46:47], v[32:33] op_sel_hi:[1,0]
	v_pk_mul_f32 v[28:29], v[32:33], v[28:29] op_sel_hi:[0,1]
	v_addc_co_u32_e32 v27, vcc, -1, v21, vcc
	v_pk_mul_f32 v[46:47], v[4:5], v[46:47]
	v_pk_mul_f32 v[28:29], v[12:13], v[28:29]
	v_cvt_pk_bf16_f32 v43, v46, v47
	v_cvt_pk_bf16_f32 v25, v28, v29
	global_store_dwordx4 v[44:45], v[40:43], off
	global_store_dwordx4 v[26:27], v[22:25], off offset:-3072
	s_add_i32 s17, s17, s32
	s_cmp_lt_i32 s17, 0x8000
	s_cselect_b32 s18, s80, 0
	s_cselect_b32 s19, s81, 0
	v_lshl_add_u64 v[20:21], v[20:21], 0, s[18:19]
	global_load_dwordx4 v[22:25], v[20:21], off
	global_load_dwordx4 v[28:31], v[20:21], off offset:1024
	s_cmp_ge_i32 s23, 0x8000
	s_cbranch_scc1 .Lnorm_s10_done
	s_waitcnt vmcnt(4)
	v_and_b32_e32 v41, 0xffff0000, v222
	v_lshlrev_b32_e32 v40, 16, v222
	v_mul_f32_e32 v0, v41, v41
	v_lshlrev_b32_e32 v42, 16, v223
	v_fmac_f32_e32 v0, v40, v40
	v_and_b32_e32 v43, 0xffff0000, v223
	v_fmac_f32_e32 v0, v42, v42
	v_lshlrev_b32_e32 v44, 16, v224
	v_fmac_f32_e32 v0, v43, v43
	v_and_b32_e32 v45, 0xffff0000, v224
	v_fmac_f32_e32 v0, v44, v44
	v_lshlrev_b32_e32 v46, 16, v225
	v_fmac_f32_e32 v0, v45, v45
	v_and_b32_e32 v47, 0xffff0000, v225
	v_fmac_f32_e32 v0, v46, v46
	v_fmac_f32_e32 v0, v47, v47
	v_lshlrev_b32_e32 v222, 16, v228
	v_and_b32_e32 v223, 0xffff0000, v228
	v_fmac_f32_e32 v0, v222, v222
	v_lshlrev_b32_e32 v224, 16, v229
	v_fmac_f32_e32 v0, v223, v223
	v_and_b32_e32 v226, 0xffff0000, v230
	v_and_b32_e32 v225, 0xffff0000, v229
	v_fmac_f32_e32 v0, v224, v224
	v_lshlrev_b32_e32 v229, 16, v230
	v_mov_b32_e32 v228, v226
	v_fmac_f32_e32 v0, v225, v225
	v_pk_mul_f32 v[48:49], v[228:229], v[228:229]
	v_and_b32_e32 v227, s0, v231
	v_add_f32_e32 v0, v49, v0
	v_add_f32_e32 v19, v48, v0
	v_and_b32_e32 v0, 0xffff0000, v231
	v_lshlrev_b32_e32 v231, 16, v231
	v_mov_b32_e32 v230, v0
	v_pk_mul_f32 v[48:49], v[230:231], v[230:231]
	v_pk_mov_b32 v[226:227], v[228:229], v[226:227] op_sel:[1,0]
	v_add_f32_e32 v19, v49, v19
	v_add_f32_e32 v19, v48, v19
	ds_bpermute_b32 v32, v33, v19
	v_pk_mov_b32 v[228:229], v[230:231], v[0:1] op_sel:[1,0]
	s_waitcnt lgkmcnt(0)
	v_add_f32_e32 v19, v19, v32
	ds_bpermute_b32 v32, v34, v19
	s_waitcnt lgkmcnt(0)
	v_add_f32_e32 v19, v19, v32
	ds_bpermute_b32 v32, v35, v19
	s_waitcnt lgkmcnt(0)
	v_add_f32_e32 v19, v19, v32
	ds_bpermute_b32 v32, v36, v19
	s_waitcnt lgkmcnt(0)
	v_add_f32_e32 v19, v19, v32
	ds_bpermute_b32 v32, v37, v19
	s_waitcnt lgkmcnt(0)
	v_add_f32_e32 v19, v19, v32
	ds_bpermute_b32 v32, v38, v19
	s_waitcnt lgkmcnt(0)
	v_add_f32_e32 v19, v19, v32
	v_fmamk_f32 v19, v19, 0x3a800000, v194
	v_cmp_gt_f32_e32 vcc, s76, v19
	v_mul_f32_e32 v32, 0x4b800000, v19
	s_nop 0
	v_cndmask_b32_e32 v19, v19, v32, vcc
	v_rsq_f32_e32 v19, v19
	s_nop 0
	v_mul_f32_e32 v32, 0x45800000, v19
	v_cndmask_b32_e32 v32, v19, v32, vcc
	v_pk_mul_f32 v[40:41], v[40:41], v[32:33] op_sel_hi:[1,0]
	v_pk_mul_f32 v[42:43], v[42:43], v[32:33] op_sel_hi:[1,0]
	v_pk_mul_f32 v[44:45], v[44:45], v[32:33] op_sel_hi:[1,0]
	v_pk_mul_f32 v[42:43], v[8:9], v[42:43]
	v_pk_mul_f32 v[40:41], v[6:7], v[40:41]
	v_pk_mul_f32 v[44:45], v[2:3], v[44:45]
	v_cvt_pk_bf16_f32 v40, v40, v41
	v_cvt_pk_bf16_f32 v41, v42, v43
	v_cvt_pk_bf16_f32 v42, v44, v45
	v_add_co_u32_e32 v44, vcc, s2, v204
	v_pk_mul_f32 v[222:223], v[222:223], v[32:33] op_sel_hi:[1,0]
	v_pk_mul_f32 v[224:225], v[224:225], v[32:33] op_sel_hi:[1,0]
	v_pk_mul_f32 v[226:227], v[32:33], v[226:227] op_sel_hi:[0,1]
	v_addc_co_u32_e32 v45, vcc, -1, v205, vcc
	v_pk_mul_f32 v[224:225], v[16:17], v[224:225]
	v_pk_mul_f32 v[222:223], v[14:15], v[222:223]
	v_pk_mul_f32 v[226:227], v[10:11], v[226:227]
	v_cvt_pk_bf16_f32 v222, v222, v223
	v_cvt_pk_bf16_f32 v223, v224, v225
	v_cvt_pk_bf16_f32 v224, v226, v227
	v_add_co_u32_e32 v226, vcc, 0xea67e000, v204
	v_pk_mul_f32 v[46:47], v[46:47], v[32:33] op_sel_hi:[1,0]
	v_pk_mul_f32 v[228:229], v[32:33], v[228:229] op_sel_hi:[0,1]
	v_addc_co_u32_e32 v227, vcc, -1, v205, vcc
	v_pk_mul_f32 v[46:47], v[4:5], v[46:47]
	v_pk_mul_f32 v[228:229], v[12:13], v[228:229]
	v_cvt_pk_bf16_f32 v43, v46, v47
	v_cvt_pk_bf16_f32 v225, v228, v229
	global_store_dwordx4 v[44:45], v[40:43], off
	global_store_dwordx4 v[226:227], v[222:225], off offset:-3072
	s_add_i32 s23, s23, s32
	s_cmp_lt_i32 s23, 0x8000
	s_cselect_b32 s18, s80, 0
	s_cselect_b32 s19, s81, 0
	v_lshl_add_u64 v[204:205], v[204:205], 0, s[18:19]
	global_load_dwordx4 v[222:225], v[204:205], off
	global_load_dwordx4 v[228:231], v[204:205], off offset:1024
	s_cmp_lt_i32 s17, 0x8000
	s_cbranch_scc1 .Lnorm_s10_loop
.Lnorm_s10_done:
.LBB0_1449:
	s_or_b64 exec, exec, s[4:5]
